# compressed branch pass 2 (importance): far blocks through a hand-written loop (same operations in the same order; K prefetched in place, Q read once, one exec region for the table writes)
# speedup vs baseline: 1.0022x; 1.0014x over previous
.LBB0_1290:
	v_mov_b32_e32 v2, v168
	s_nop 1
	v_permlane32_swap_b32_e32 v168, v2
	v_add_f32_e32 v2, v168, v2
	v_div_scale_f32 v3, s[4:5], v2, v2, 1.0
	v_rcp_f32_e32 v4, v3
	v_lshlrev_b32_e32 v181, 2, v231
	s_waitcnt vmcnt(0)
	v_mov_b32_e32 v73, 0
	s_add_i32 s13, s10, -8
	v_fma_f32 v5, -v3, v4, 1.0
	v_fmac_f32_e32 v4, v5, v4
	v_div_scale_f32 v5, vcc, 1.0, v2, 1.0
	v_mul_f32_e32 v6, v5, v4
	v_fma_f32 v7, -v3, v6, v5
	v_fmac_f32_e32 v6, v7, v4
	v_fma_f32 v3, -v3, v6, v5
	v_div_fmas_f32 v3, v3, v4, v6
	v_div_fixup_f32 v3, v3, v2, 1.0
	v_cmp_lt_f32_e32 vcc, 0, v2
	v_cmp_gt_u32_e64 s[8:9], 32, v229
	v_cmp_eq_u32_e64 s[10:11], 0, v227
	v_cndmask_b32_e32 v70, 0, v3, vcc
	v_mul_f32_e32 v10, v209, v70
	v_pk_mul_f32 v[4:5], v[50:51], v[10:11] op_sel_hi:[1,0]
	v_pk_mul_f32 v[2:3], v[34:35], v[10:11] op_sel_hi:[1,0]
	v_cvt_pk_bf16_f32 v6, v4, v5
	v_pk_mul_f32 v[4:5], v[36:37], v[10:11] op_sel_hi:[1,0]
	v_cvt_pk_bf16_f32 v2, v2, v3
	v_cvt_pk_bf16_f32 v3, v4, v5
	v_pk_mul_f32 v[4:5], v[52:53], v[10:11] op_sel_hi:[1,0]
	v_pk_mul_f32 v[12:13], v[40:41], v[10:11] op_sel_hi:[1,0]
	v_cvt_pk_bf16_f32 v7, v4, v5
	v_pk_mul_f32 v[4:5], v[38:39], v[10:11] op_sel_hi:[1,0]
	v_pk_mul_f32 v[8:9], v[54:55], v[10:11] op_sel_hi:[1,0]
	v_cvt_pk_bf16_f32 v4, v4, v5
	v_cvt_pk_bf16_f32 v5, v12, v13
	v_pk_mul_f32 v[12:13], v[56:57], v[10:11] op_sel_hi:[1,0]
	v_cvt_pk_bf16_f32 v8, v8, v9
	v_cvt_pk_bf16_f32 v9, v12, v13
	global_store_dwordx4 v[178:179], v[2:5], off offset:64
	global_store_dwordx4 v[178:179], v[6:9], off offset:96
	v_pk_mul_f32 v[12:13], v[48:49], v[10:11] op_sel_hi:[1,0]
	v_pk_mul_f32 v[4:5], v[58:59], v[10:11] op_sel_hi:[1,0]
	v_pk_mul_f32 v[2:3], v[42:43], v[10:11] op_sel_hi:[1,0]
	v_cvt_pk_bf16_f32 v6, v4, v5
	v_pk_mul_f32 v[4:5], v[44:45], v[10:11] op_sel_hi:[1,0]
	v_cvt_pk_bf16_f32 v2, v2, v3
	v_cvt_pk_bf16_f32 v3, v4, v5
	v_pk_mul_f32 v[4:5], v[60:61], v[10:11] op_sel_hi:[1,0]
	v_pk_mul_f32 v[8:9], v[62:63], v[10:11] op_sel_hi:[1,0]
	v_cvt_pk_bf16_f32 v7, v4, v5
	v_pk_mul_f32 v[4:5], v[46:47], v[10:11] op_sel_hi:[1,0]
	v_pk_mul_f32 v[10:11], v[64:65], v[10:11] op_sel_hi:[1,0]
	v_cvt_pk_bf16_f32 v4, v4, v5
	v_cvt_pk_bf16_f32 v5, v12, v13
	v_cvt_pk_bf16_f32 v8, v8, v9
	v_cvt_pk_bf16_f32 v9, v10, v11
	global_store_dwordx4 v[178:179], v[2:5], off offset:80
	global_store_dwordx4 v[178:179], v[6:9], off offset:112
	v_cmp_neq_f32_e32 vcc, s68, v167
	v_lshl_or_b32 v2, v228, 9, v181
	v_mov_b32_e32 v209, v208
	v_cndmask_b32_e32 v71, 0, v167, vcc
	v_add_u32_e32 v72, s94, v2
	s_mov_b64 s[14:15], 0
	s_mov_b32 s18, 0xa800
	s_cmp_gt_i32 s13, 63
	s_cbranch_scc0 .LBB0_1292
	v_readfirstlane_b32 s22, v162
	v_readfirstlane_b32 s23, v163
	s_add_u32 s22, s22, 0x7e00000
	s_addc_u32 s23, s23, 0
	global_load_dwordx4 v[34:37], v194, s[22:23]
	global_load_dwordx4 v[38:41], v194, s[22:23] offset:1024
	global_load_dwordx4 v[42:45], v194, s[22:23] offset:2048
	global_load_dwordx4 v[46:49], v194, s[22:23] offset:3072
	global_load_dwordx4 v[50:53], v200, s[22:23]
	global_load_dwordx4 v[54:57], v202, s[22:23]
	global_load_dwordx4 v[58:61], v204, s[22:23]
	global_load_dwordx4 v[62:65], v206, s[22:23]
	ds_read_b128 v[234:237], v224
	ds_read_b128 v[238:241], v224 offset:32
	ds_read_b128 v[242:245], v224 offset:64
	ds_read_b128 v[246:249], v224 offset:96
	v_mov_b32_e32 v76, v71
	v_mov_b32_e32 v79, v73
	s_waitcnt lgkmcnt(0)
.Lc2_loop:
	s_add_i32 s4, s18, 0xffff587f
	s_cmp_lt_i32 s4, s13
	s_cselect_b32 s24, 1, 0
	s_waitcnt vmcnt(0)
	v_mfma_f32_32x32x16_bf16 v[2:17], v[34:37], v[234:237], 0
	v_mfma_f32_32x32x16_bf16 v[18:33], v[50:53], v[234:237], 0
	v_mfma_f32_32x32x16_bf16 v[2:17], v[38:41], v[238:241], v[2:17]
	v_mfma_f32_32x32x16_bf16 v[18:33], v[54:57], v[238:241], v[18:33]
	v_mfma_f32_32x32x16_bf16 v[2:17], v[42:45], v[242:245], v[2:17]
	v_mfma_f32_32x32x16_bf16 v[18:33], v[58:61], v[242:245], v[18:33]
	v_mfma_f32_32x32x16_bf16 v[2:17], v[46:49], v[246:249], v[2:17]
	v_mfma_f32_32x32x16_bf16 v[18:33], v[62:65], v[246:249], v[18:33]
	s_cmp_lg_u32 s24, 0
	s_cbranch_scc0 .Lc2_nok
	s_add_u32 s22, s22, 0x2000
	s_addc_u32 s23, s23, 0
	global_load_dwordx4 v[34:37], v194, s[22:23]
	global_load_dwordx4 v[38:41], v194, s[22:23] offset:1024
	global_load_dwordx4 v[42:45], v194, s[22:23] offset:2048
	global_load_dwordx4 v[46:49], v194, s[22:23] offset:3072
	global_load_dwordx4 v[50:53], v200, s[22:23]
	global_load_dwordx4 v[54:57], v202, s[22:23]
	global_load_dwordx4 v[58:61], v204, s[22:23]
	global_load_dwordx4 v[62:65], v206, s[22:23]
	s_branch .Lc2_k

.Lc2_k:
	v_add_u32_e32 v91, s18, v72
	s_nop 1
	v_pk_fma_f32 v[2:3], v[2:3], s[28:29], v[208:209] op_sel_hi:[1,0,1]
	v_pk_fma_f32 v[4:5], v[4:5], s[28:29], v[208:209] op_sel_hi:[1,0,1]
	v_pk_fma_f32 v[6:7], v[6:7], s[28:29], v[208:209] op_sel_hi:[1,0,1]
	v_pk_fma_f32 v[8:9], v[8:9], s[28:29], v[208:209] op_sel_hi:[1,0,1]
	v_pk_fma_f32 v[10:11], v[10:11], s[28:29], v[208:209] op_sel_hi:[1,0,1]
	v_pk_fma_f32 v[12:13], v[12:13], s[28:29], v[208:209] op_sel_hi:[1,0,1]
	v_pk_fma_f32 v[14:15], v[14:15], s[28:29], v[208:209] op_sel_hi:[1,0,1]
	v_pk_fma_f32 v[16:17], v[16:17], s[28:29], v[208:209] op_sel_hi:[1,0,1]
	v_pk_fma_f32 v[18:19], v[18:19], s[28:29], v[208:209] op_sel_hi:[1,0,1]
	v_pk_fma_f32 v[20:21], v[20:21], s[28:29], v[208:209] op_sel_hi:[1,0,1]
	v_pk_fma_f32 v[22:23], v[22:23], s[28:29], v[208:209] op_sel_hi:[1,0,1]
	v_pk_fma_f32 v[24:25], v[24:25], s[28:29], v[208:209] op_sel_hi:[1,0,1]
	v_pk_fma_f32 v[26:27], v[26:27], s[28:29], v[208:209] op_sel_hi:[1,0,1]
	v_pk_fma_f32 v[28:29], v[28:29], s[28:29], v[208:209] op_sel_hi:[1,0,1]
	v_pk_fma_f32 v[30:31], v[30:31], s[28:29], v[208:209] op_sel_hi:[1,0,1]
	v_pk_fma_f32 v[32:33], v[32:33], s[28:29], v[208:209] op_sel_hi:[1,0,1]
	v_pk_add_f32 v[2:3], v[2:3], v[76:77] op_sel_hi:[1,0] neg_lo:[0,1] neg_hi:[0,1]
	v_pk_add_f32 v[4:5], v[4:5], v[76:77] op_sel_hi:[1,0] neg_lo:[0,1] neg_hi:[0,1]
	v_pk_add_f32 v[6:7], v[6:7], v[76:77] op_sel_hi:[1,0] neg_lo:[0,1] neg_hi:[0,1]
	v_pk_add_f32 v[8:9], v[8:9], v[76:77] op_sel_hi:[1,0] neg_lo:[0,1] neg_hi:[0,1]
	v_pk_add_f32 v[10:11], v[10:11], v[76:77] op_sel_hi:[1,0] neg_lo:[0,1] neg_hi:[0,1]
	v_pk_add_f32 v[12:13], v[12:13], v[76:77] op_sel_hi:[1,0] neg_lo:[0,1] neg_hi:[0,1]
	v_pk_add_f32 v[14:15], v[14:15], v[76:77] op_sel_hi:[1,0] neg_lo:[0,1] neg_hi:[0,1]
	v_pk_add_f32 v[16:17], v[16:17], v[76:77] op_sel_hi:[1,0] neg_lo:[0,1] neg_hi:[0,1]
	v_pk_add_f32 v[18:19], v[18:19], v[76:77] op_sel_hi:[1,0] neg_lo:[0,1] neg_hi:[0,1]
	v_pk_add_f32 v[20:21], v[20:21], v[76:77] op_sel_hi:[1,0] neg_lo:[0,1] neg_hi:[0,1]
	v_pk_add_f32 v[22:23], v[22:23], v[76:77] op_sel_hi:[1,0] neg_lo:[0,1] neg_hi:[0,1]
	v_pk_add_f32 v[24:25], v[24:25], v[76:77] op_sel_hi:[1,0] neg_lo:[0,1] neg_hi:[0,1]
	v_pk_add_f32 v[26:27], v[26:27], v[76:77] op_sel_hi:[1,0] neg_lo:[0,1] neg_hi:[0,1]
	v_pk_add_f32 v[28:29], v[28:29], v[76:77] op_sel_hi:[1,0] neg_lo:[0,1] neg_hi:[0,1]
	v_pk_add_f32 v[30:31], v[30:31], v[76:77] op_sel_hi:[1,0] neg_lo:[0,1] neg_hi:[0,1]
	v_pk_add_f32 v[32:33], v[32:33], v[76:77] op_sel_hi:[1,0] neg_lo:[0,1] neg_hi:[0,1]
	v_exp_f32_e32 v2, v2
	v_exp_f32_e32 v3, v3
	v_exp_f32_e32 v4, v4
	v_exp_f32_e32 v5, v5
	v_exp_f32_e32 v6, v6
	v_exp_f32_e32 v7, v7
	v_exp_f32_e32 v8, v8
	v_exp_f32_e32 v9, v9
	v_exp_f32_e32 v10, v10
	v_exp_f32_e32 v11, v11
	v_exp_f32_e32 v12, v12
	v_exp_f32_e32 v13, v13
	v_exp_f32_e32 v14, v14
	v_exp_f32_e32 v15, v15
	v_exp_f32_e32 v16, v16
	v_exp_f32_e32 v17, v17
	v_exp_f32_e32 v18, v18
	v_exp_f32_e32 v19, v19
	v_exp_f32_e32 v20, v20
	v_exp_f32_e32 v21, v21
	v_exp_f32_e32 v22, v22
	v_exp_f32_e32 v23, v23
	v_exp_f32_e32 v24, v24
	v_exp_f32_e32 v25, v25
	v_exp_f32_e32 v26, v26
	v_exp_f32_e32 v27, v27
	v_exp_f32_e32 v28, v28
	v_exp_f32_e32 v29, v29
	v_exp_f32_e32 v30, v30
	v_exp_f32_e32 v31, v31
	v_exp_f32_e32 v32, v32
	v_exp_f32_e32 v33, v33
	v_mul_f32_e32 v3, v70, v3
	v_mul_f32_e32 v5, v70, v5
	v_fmac_f32_e32 v3, v70, v2
	v_fma_f32 v2, v70, v4, v5
	v_add_f32_e32 v74, v3, v2
	v_mov_b32_e32 v75, v5
	s_nop 1
	v_permlane32_swap_b32_e32 v5, v75
	v_cndmask_b32_e64 v78, v5, v75, s[6:7]
	v_cndmask_b32_e64 v88, v78, v79, s[8:9]
	v_add_f32_e32 v74, v74, v88
	v_mov_b32_e32 v79, v78
	s_nop 0
	v_add_f32_dpp v89, v74, v74 quad_perm:[1,0,3,2] row_mask:0xf bank_mask:0xf bound_ctrl:1
	v_mov_b32_e32 v90, 0
	s_nop 0
	v_mov_b32_dpp v90, v89 quad_perm:[2,3,0,1] row_mask:0xf bank_mask:0xf
	s_nop 0
	v_add_f32_e32 v80, v89, v90
	v_mul_f32_e32 v7, v70, v7
	v_mul_f32_e32 v9, v70, v9
	v_fmac_f32_e32 v7, v70, v6
	v_fma_f32 v6, v70, v8, v9
	v_add_f32_e32 v74, v7, v6
	v_mov_b32_e32 v75, v9
	s_nop 1
	v_permlane32_swap_b32_e32 v9, v75
	v_cndmask_b32_e64 v78, v9, v75, s[6:7]
	v_cndmask_b32_e64 v88, v78, v79, s[8:9]
	v_add_f32_e32 v74, v74, v88
	v_mov_b32_e32 v79, v78
	s_nop 0
	v_add_f32_dpp v89, v74, v74 quad_perm:[1,0,3,2] row_mask:0xf bank_mask:0xf bound_ctrl:1
	v_mov_b32_e32 v90, 0
	s_nop 0
	v_mov_b32_dpp v90, v89 quad_perm:[2,3,0,1] row_mask:0xf bank_mask:0xf
	s_nop 0
	v_add_f32_e32 v81, v89, v90
	v_mul_f32_e32 v11, v70, v11
	v_mul_f32_e32 v13, v70, v13
	v_fmac_f32_e32 v11, v70, v10
	v_fma_f32 v10, v70, v12, v13
	v_add_f32_e32 v74, v11, v10
	v_mov_b32_e32 v75, v13
	s_nop 1
	v_permlane32_swap_b32_e32 v13, v75
	v_cndmask_b32_e64 v78, v13, v75, s[6:7]
	v_cndmask_b32_e64 v88, v78, v79, s[8:9]
	v_add_f32_e32 v74, v74, v88
	v_mov_b32_e32 v79, v78
	s_nop 0
	v_add_f32_dpp v89, v74, v74 quad_perm:[1,0,3,2] row_mask:0xf bank_mask:0xf bound_ctrl:1
	v_mov_b32_e32 v90, 0
	s_nop 0
	v_mov_b32_dpp v90, v89 quad_perm:[2,3,0,1] row_mask:0xf bank_mask:0xf
	s_nop 0
	v_add_f32_e32 v82, v89, v90
	v_mul_f32_e32 v15, v70, v15
	v_mul_f32_e32 v17, v70, v17
	v_fmac_f32_e32 v15, v70, v14
	v_fma_f32 v14, v70, v16, v17
	v_add_f32_e32 v74, v15, v14
	v_mov_b32_e32 v75, v17
	s_nop 1
	v_permlane32_swap_b32_e32 v17, v75
	v_cndmask_b32_e64 v78, v17, v75, s[6:7]
	v_cndmask_b32_e64 v88, v78, v79, s[8:9]
	v_add_f32_e32 v74, v74, v88
	v_mov_b32_e32 v79, v78
	s_nop 0
	v_add_f32_dpp v89, v74, v74 quad_perm:[1,0,3,2] row_mask:0xf bank_mask:0xf bound_ctrl:1
	v_mov_b32_e32 v90, 0
	s_nop 0
	v_mov_b32_dpp v90, v89 quad_perm:[2,3,0,1] row_mask:0xf bank_mask:0xf
	s_nop 0
	v_add_f32_e32 v83, v89, v90
	v_mul_f32_e32 v19, v70, v19
	v_mul_f32_e32 v21, v70, v21
	v_fmac_f32_e32 v19, v70, v18
	v_fma_f32 v18, v70, v20, v21
	v_add_f32_e32 v74, v19, v18
	v_mov_b32_e32 v75, v21
	s_nop 1
	v_permlane32_swap_b32_e32 v21, v75
	v_cndmask_b32_e64 v78, v21, v75, s[6:7]
	v_cndmask_b32_e64 v88, v78, v79, s[8:9]
	v_add_f32_e32 v74, v74, v88
	v_mov_b32_e32 v79, v78
	s_nop 0
	v_add_f32_dpp v89, v74, v74 quad_perm:[1,0,3,2] row_mask:0xf bank_mask:0xf bound_ctrl:1
	v_mov_b32_e32 v90, 0
	s_nop 0
	v_mov_b32_dpp v90, v89 quad_perm:[2,3,0,1] row_mask:0xf bank_mask:0xf
	s_nop 0
	v_add_f32_e32 v84, v89, v90
	v_mul_f32_e32 v23, v70, v23
	v_mul_f32_e32 v25, v70, v25
	v_fmac_f32_e32 v23, v70, v22
	v_fma_f32 v22, v70, v24, v25
	v_add_f32_e32 v74, v23, v22
	v_mov_b32_e32 v75, v25
	s_nop 1
	v_permlane32_swap_b32_e32 v25, v75
	v_cndmask_b32_e64 v78, v25, v75, s[6:7]
	v_cndmask_b32_e64 v88, v78, v79, s[8:9]
	v_add_f32_e32 v74, v74, v88
	v_mov_b32_e32 v79, v78
	s_nop 0
	v_add_f32_dpp v89, v74, v74 quad_perm:[1,0,3,2] row_mask:0xf bank_mask:0xf bound_ctrl:1
	v_mov_b32_e32 v90, 0
	s_nop 0
	v_mov_b32_dpp v90, v89 quad_perm:[2,3,0,1] row_mask:0xf bank_mask:0xf
	s_nop 0
	v_add_f32_e32 v85, v89, v90
	v_mul_f32_e32 v27, v70, v27
	v_mul_f32_e32 v29, v70, v29
	v_fmac_f32_e32 v27, v70, v26
	v_fma_f32 v26, v70, v28, v29
	v_add_f32_e32 v74, v27, v26
	v_mov_b32_e32 v75, v29
	s_nop 1
	v_permlane32_swap_b32_e32 v29, v75
	v_cndmask_b32_e64 v78, v29, v75, s[6:7]
	v_cndmask_b32_e64 v88, v78, v79, s[8:9]
	v_add_f32_e32 v74, v74, v88
	v_mov_b32_e32 v79, v78
	s_nop 0
	v_add_f32_dpp v89, v74, v74 quad_perm:[1,0,3,2] row_mask:0xf bank_mask:0xf bound_ctrl:1
	v_mov_b32_e32 v90, 0
	s_nop 0
	v_mov_b32_dpp v90, v89 quad_perm:[2,3,0,1] row_mask:0xf bank_mask:0xf
	s_nop 0
	v_add_f32_e32 v86, v89, v90
	v_mul_f32_e32 v31, v70, v31
	v_mul_f32_e32 v33, v70, v33
	v_fmac_f32_e32 v31, v70, v30
	v_fma_f32 v30, v70, v32, v33
	v_add_f32_e32 v74, v31, v30
	v_mov_b32_e32 v75, v33
	s_nop 1
	v_permlane32_swap_b32_e32 v33, v75
	v_cndmask_b32_e64 v78, v33, v75, s[6:7]
	v_cndmask_b32_e64 v88, v78, v79, s[8:9]
	v_add_f32_e32 v74, v74, v88
	v_mov_b32_e32 v79, v78
	s_nop 0
	v_add_f32_dpp v89, v74, v74 quad_perm:[1,0,3,2] row_mask:0xf bank_mask:0xf bound_ctrl:1
	v_mov_b32_e32 v90, 0
	s_nop 0
	v_mov_b32_dpp v90, v89 quad_perm:[2,3,0,1] row_mask:0xf bank_mask:0xf
	s_nop 0
	v_add_f32_e32 v87, v89, v90
	s_and_saveexec_b64 s[16:17], s[10:11]
	ds_write_b32 v91, v80
	ds_write_b32 v91, v81 offset:8
	ds_write_b32 v91, v82 offset:16
	ds_write_b32 v91, v83 offset:24
	ds_write_b32 v91, v84 offset:32
	ds_write_b32 v91, v85 offset:40
	ds_write_b32 v91, v86 offset:48
	ds_write_b32 v91, v87 offset:56
	s_or_b64 exec, exec, s[16:17]
	s_add_u32 s14, s14, 0x2000
	s_addc_u32 s15, s15, 0
	s_add_i32 s18, s18, 64
	v_add_u32_e32 v161, 0xfffffc00, v161
	s_cmp_lg_u32 s24, 0
	s_cbranch_scc1 .Lc2_loop
	v_mov_b32_e32 v73, v79
	s_branch .LBB0_1292
